# attention: wave-uniform branch skips the -1e30 mask selects on unmasked tiles (64 fewer VALU per 2-tile iteration); on top of GEMM saddr/dsbase/no-setprio
# speedup vs baseline: 1.0204x; 1.0074x over previous
; __device__ __forceinline__ void finishSM(f32x16& p0, f32x16& p1, float alpha, float& l_reg, bf16x8& pa0, bf16x8& pa1, bf16x8& pa2, bf16x8& pa3) {
; #pragma unroll
;     for (int r = 0; r < 16; ++r) p1[r] = __builtin_amdgcn_exp2f(p1[r]);
;     float ps = 0;
; #pragma unroll
;     for (int r = 0; r < 16; ++r) ps += p0[r];
; #pragma unroll
;     for (int r = 0; r < 16; ++r) ps += p1[r];
;     { auto rr = __builtin_amdgcn_permlane32_swap(__float_as_uint(ps), __float_as_uint(ps), false, false);
;       ps = __uint_as_float(rr[0]) + __uint_as_float(rr[1]); }
;     l_reg = l_reg * alpha + ps;
;     ...
;     PK4(p0, 0, pa0); PK4(p0, 8, pa1); PK4(p1, 0, pa2); PK4(p1, 8, pa3);
;     ...
; }
; __device__ __forceinline__ void qkt(f32x16& p0, f32x16& p1, const char* Ks, const bf16x8* qr, int r32, int hi) {
;     p0 = f32x16{}; p1 = f32x16{};
; #pragma unroll
;     for (int d0 = 0; d0 < 8; ++d0) { int cb = (d0 * 16 + hi * 8) * 2;
;         bf16x8 b0 = *reinterpret_cast<const bf16x8*>(Ks + KSWZ(r32, cb));
;         bf16x8 b1 = *reinterpret_cast<const bf16x8*>(Ks + KSWZ(32 + r32, cb));
;         p0 = __builtin_amdgcn_mfma_f32_32x32x16_bf16(b0, qr[d0], p0, 0, 0, 0);
;         p1 = __builtin_amdgcn_mfma_f32_32x32x16_bf16(b1, qr[d0], p1, 0, 0, 0); }
; }
.LBB0_280:
	s_add_i32 s9, s25, -1
	ds_read_b128 v[64:67], v215 offset:49152
	ds_read_b128 v[68:71], v215 offset:57344
	ds_read_b128 v[224:227], v222 offset:49152
	ds_read_b128 v[236:239], v222 offset:57344
	v_add_f32_e32 v160, 0, v174
	v_add_f32_e32 v160, v198, v160
	s_waitcnt lgkmcnt(3)
	v_mfma_f32_32x32x16_bf16 v[80:95], v[64:67], v[124:127], 0
	v_add_f32_e32 v160, v161, v160
	v_add_f32_e32 v160, v175, v160
	v_add_f32_e32 v160, v162, v160
	v_add_f32_e32 v160, v173, v160
	v_add_f32_e32 v160, v163, v160
	v_add_f32_e32 v160, v172, v160
	v_add_f32_e32 v160, v164, v160
	s_waitcnt lgkmcnt(2)
	v_mfma_f32_32x32x16_bf16 v[64:79], v[68:71], v[124:127], 0
	v_add_f32_e32 v160, v171, v160
	v_add_f32_e32 v160, v165, v160
	v_add_f32_e32 v160, v170, v160
	v_exp_f32_e32 v156, v156
	v_add_f32_e32 v160, v166, v160
	v_exp_f32_e32 v157, v157
	v_add_f32_e32 v160, v169, v160
	s_waitcnt lgkmcnt(1)
	v_mfma_f32_32x32x16_bf16 v[80:95], v[224:227], v[120:123], v[80:95]
	v_exp_f32_e32 v154, v154
	v_add_f32_e32 v160, v167, v160
	v_exp_f32_e32 v155, v155
	v_add_f32_e32 v160, v168, v160
	v_exp_f32_e32 v148, v148
	v_add_f32_e32 v160, v156, v160
	v_exp_f32_e32 v149, v149
	s_waitcnt lgkmcnt(0)
	v_mfma_f32_32x32x16_bf16 v[64:79], v[236:239], v[120:123], v[64:79]
	ds_read_b128 v[224:227], v221 offset:49152
	ds_read_b128 v[236:239], v221 offset:57344
	v_add_f32_e32 v160, v157, v160
	v_exp_f32_e32 v146, v146
	v_add_f32_e32 v160, v154, v160
	v_exp_f32_e32 v147, v147
	v_add_f32_e32 v160, v155, v160
	v_exp_f32_e32 v144, v144
	s_waitcnt lgkmcnt(1)
	v_mfma_f32_32x32x16_bf16 v[80:95], v[224:227], v[116:119], v[80:95]
	v_add_f32_e32 v160, v148, v160
	v_exp_f32_e32 v145, v145
	v_add_f32_e32 v160, v149, v160
	v_exp_f32_e32 v158, v158
	v_add_f32_e32 v160, v146, v160
	v_exp_f32_e32 v159, v159
	v_add_f32_e32 v160, v147, v160
	s_waitcnt lgkmcnt(0)
	v_mfma_f32_32x32x16_bf16 v[64:79], v[236:239], v[116:119], v[64:79]
	ds_read_b128 v[224:227], v218 offset:49152
	ds_read_b128 v[236:239], v218 offset:57344
	v_exp_f32_e32 v152, v152
	v_add_f32_e32 v160, v144, v160
	v_exp_f32_e32 v153, v153
	v_add_f32_e32 v160, v145, v160
	v_exp_f32_e32 v150, v150
	v_add_f32_e32 v160, v158, v160
	s_waitcnt lgkmcnt(1)
	v_mfma_f32_32x32x16_bf16 v[80:95], v[224:227], v[112:115], v[80:95]
	v_exp_f32_e32 v151, v151
	v_add_f32_e32 v160, v159, v160
	v_add_f32_e32 v160, v152, v160
	v_add_f32_e32 v160, v153, v160
	v_add_f32_e32 v160, v150, v160
	s_waitcnt lgkmcnt(0)
	v_mfma_f32_32x32x16_bf16 v[64:79], v[236:239], v[112:115], v[64:79]
	ds_read_b128 v[224:227], v217 offset:49152
	ds_read_b128 v[236:239], v217 offset:57344
	s_waitcnt lgkmcnt(1)
	v_mfma_f32_32x32x16_bf16 v[80:95], v[224:227], v[108:111], v[80:95]
	s_waitcnt lgkmcnt(0)
	v_mfma_f32_32x32x16_bf16 v[64:79], v[236:239], v[108:111], v[64:79]
	ds_read_b128 v[224:227], v216 offset:49152
	ds_read_b128 v[236:239], v216 offset:57344
	s_waitcnt lgkmcnt(1)
	v_mfma_f32_32x32x16_bf16 v[80:95], v[224:227], v[104:107], v[80:95]
	s_waitcnt lgkmcnt(0)
	v_mfma_f32_32x32x16_bf16 v[64:79], v[236:239], v[104:107], v[64:79]
	ds_read_b128 v[224:227], v219 offset:49152
	ds_read_b128 v[236:239], v219 offset:57344
	s_waitcnt lgkmcnt(1)
	v_mfma_f32_32x32x16_bf16 v[80:95], v[224:227], v[100:103], v[80:95]
	s_waitcnt lgkmcnt(0)
	v_mfma_f32_32x32x16_bf16 v[64:79], v[236:239], v[100:103], v[64:79]
	ds_read_b128 v[224:227], v220 offset:49152
	ds_read_b128 v[236:239], v220 offset:57344
	s_waitcnt lgkmcnt(1)
	v_mfma_f32_32x32x16_bf16 v[80:95], v[224:227], v[96:99], v[80:95]
	v_add_f32_e32 v224, v151, v160
	v_mov_b32_e32 v225, v224
	v_cvt_pk_bf16_f32 v160, v174, v198
	v_cvt_pk_bf16_f32 v161, v161, v175
	v_cvt_pk_bf16_f32 v162, v162, v173
	s_nop 1
	v_permlane32_swap_b32_e32 v224, v225
	s_waitcnt lgkmcnt(0)
; #define SBAR() __builtin_amdgcn_sched_barrier(0)
; __device__ __forceinline__ void partialSM(f32x16& p0, f32x16& p1, float& m_reg, float& mn, float& alpha, bool msk) {
;     constexpr float C = SCALE * 1.4426950408889634f;
;     if (msk) {
; #pragma unroll
;         for (int r = 0; r < 16; ++r) { p0[r] = -1e30f; p1[r] = -1e30f; }
;     }
;     float pmax = p0[0];
; #pragma unroll
;     for (int r = 1; r < 16; ++r) pmax = fmaxf(pmax, p0[r]);
; #pragma unroll
;     for (int r = 0; r < 16; ++r) pmax = fmaxf(pmax, p1[r]);
;     { auto rr = __builtin_amdgcn_permlane32_swap(__float_as_uint(pmax), __float_as_uint(pmax), false, false);
;       pmax = fmaxf(__uint_as_float(rr[0]), __uint_as_float(rr[1])); }
;     if (__builtin_expect(__all(pmax - m_reg <= THR / SCALE), 1)) { mn = m_reg; alpha = 1.f; }
;     else { mn = fmaxf(m_reg, pmax); alpha = __builtin_amdgcn_exp2f((m_reg - mn) * C); m_reg = mn; }
; template <int D0> __device__ __forceinline__ void pv_one(f32x16& od, int vb, bf16x8 pa0, bf16x8 pa1, bf16x8 pa2, bf16x8 pa3) {
;     const s16x4 l0 = tr_read<v_rd_off(D0, 0, 0)>(vb), h0 = tr_read<v_rd_off(D0, 0, 1)>(vb), l1 = tr_read<v_rd_off(D0, 1, 0)>(vb), h1 = tr_read<v_rd_off(D0, 1, 1)>(vb);
;     const s16x4 l2 = tr_read<v_rd_off(D0, 2, 0)>(vb), h2 = tr_read<v_rd_off(D0, 2, 1)>(vb), l3 = tr_read<v_rd_off(D0, 3, 0)>(vb), h3 = tr_read<v_rd_off(D0, 3, 1)>(vb);
;     asm volatile("s_waitcnt lgkmcnt(0)" ::: "memory"); SBAR();
;     ...
;     od = __builtin_amdgcn_mfma_f32_32x32x16_bf16(pa0, PK(l0, h0), od, 0, 0, 0);
;     od = __builtin_amdgcn_mfma_f32_32x32x16_bf16(pa1, PK(l1, h1), od, 0, 0, 0);
;     od = __builtin_amdgcn_mfma_f32_32x32x16_bf16(pa2, PK(l2, h2), od, 0, 0, 0);
;     od = __builtin_amdgcn_mfma_f32_32x32x16_bf16(pa3, PK(l3, h3), od, 0, 0, 0);
;     ...
; }
; __device__ __forceinline__ void pv_d0(f32x16* o, int vb, bf16x8 pa0, bf16x8 pa1, bf16x8 pa2, bf16x8 pa3) {
;     pv_one<0>(o[0], vb, pa0, pa1, pa2, pa3); pv_one<1>(o[1], vb, pa0, pa1, pa2, pa3); pv_one<2>(o[2], vb, pa0, pa1, pa2, pa3); pv_one<3>(o[3], vb, pa0, pa1, pa2, pa3);
	v_mfma_f32_32x32x16_bf16 v[64:79], v[236:239], v[96:99], v[64:79]
	v_cvt_pk_bf16_f32 v163, v163, v172
	v_permlane32_swap_b32_e32 v160, v162
	v_cvt_pk_bf16_f32 v164, v164, v171
	v_cvt_pk_bf16_f32 v165, v165, v170
	v_cvt_pk_bf16_f32 v166, v166, v169
	v_cvt_pk_bf16_f32 v167, v167, v168
	v_cvt_pk_bf16_f32 v168, v156, v157
	v_cvt_pk_bf16_f32 v169, v154, v155
	v_cvt_pk_bf16_f32 v170, v148, v149
	v_cvt_pk_bf16_f32 v171, v146, v147
	v_cvt_pk_bf16_f32 v172, v144, v145
	v_cvt_pk_bf16_f32 v173, v158, v159
	v_cvt_pk_bf16_f32 v174, v152, v153
	v_cvt_pk_bf16_f32 v175, v150, v151
	v_permlane32_swap_b32_e32 v161, v163
	v_permlane32_swap_b32_e32 v164, v166
	v_permlane32_swap_b32_e32 v165, v167
	v_permlane32_swap_b32_e32 v168, v170
	v_permlane32_swap_b32_e32 v169, v171
	v_permlane32_swap_b32_e32 v172, v174
	v_permlane32_swap_b32_e32 v173, v175
	v_lshl_add_u64 v[200:201], v[192:193], 0, v[188:189]
	s_mov_b32 s10, 0x1d242000
	v_add_co_u32_e32 v144, vcc, s10, v200
	s_mov_b32 s10, 0x1d2a2000
	s_nop 0
	v_addc_co_u32_e32 v145, vcc, 0, v201, vcc
	v_add_co_u32_e32 v148, vcc, s10, v200
	v_lshl_add_u64 v[198:199], v[194:195], 0, v[188:189]
	s_nop 0
	v_addc_co_u32_e32 v149, vcc, 0, v201, vcc
	s_mov_b32 s10, 0x1d241000
	v_add_co_u32_e32 v152, vcc, s10, v198
	s_mov_b32 s10, 0x1d2a1000
	s_nop 0
	v_addc_co_u32_e32 v153, vcc, 0, v199, vcc
	v_add_co_u32_e32 v156, vcc, s10, v198
	global_load_dwordx4 v[144:147], v[144:145], off
	s_nop 0
	global_load_dwordx4 v[148:151], v[148:149], off
	v_addc_co_u32_e32 v157, vcc, 0, v199, vcc
	global_load_dwordx4 v[152:155], v[152:153], off
	s_nop 0
	global_load_dwordx4 v[156:159], v[156:157], off
	ds_read_b64_tr_b16 v[236:237], v209 offset:0
	ds_read_b64_tr_b16 v[238:239], v209 offset:0x800
	ds_read_b64_tr_b16 v[240:241], v209 offset:0x1000
	ds_read_b64_tr_b16 v[242:243], v209 offset:0x1800
	ds_read_b64_tr_b16 v[244:245], v209 offset:0x2000
	ds_read_b64_tr_b16 v[246:247], v209 offset:0x2800
	ds_read_b64_tr_b16 v[248:249], v209 offset:0x3000
	ds_read_b64_tr_b16 v[250:251], v209 offset:0x3800
	s_waitcnt lgkmcnt(0)
	s_nop 0
	v_mfma_f32_32x32x16_bf16 v[0:15], v[160:163], v[236:239], v[0:15]
	ds_read_b64_tr_b16 v[236:237], v209 offset:0x200
	ds_read_b64_tr_b16 v[238:239], v209 offset:0xa00
	v_mfma_f32_32x32x16_bf16 v[0:15], v[164:167], v[240:243], v[0:15]
	ds_read_b64_tr_b16 v[240:241], v209 offset:0x1200
	ds_read_b64_tr_b16 v[242:243], v209 offset:0x1a00
	v_mfma_f32_32x32x16_bf16 v[0:15], v[168:171], v[244:247], v[0:15]
	ds_read_b64_tr_b16 v[244:245], v209 offset:0x2200
	ds_read_b64_tr_b16 v[246:247], v209 offset:0x2a00
	v_mfma_f32_32x32x16_bf16 v[0:15], v[172:175], v[248:251], v[0:15]
	ds_read_b64_tr_b16 v[248:249], v209 offset:0x3200
	ds_read_b64_tr_b16 v[250:251], v209 offset:0x3a00
	s_waitcnt lgkmcnt(0)
	v_mfma_f32_32x32x16_bf16 v[48:63], v[160:163], v[236:239], v[48:63]
	ds_read_b64_tr_b16 v[236:237], v209 offset:0x400
	ds_read_b64_tr_b16 v[238:239], v209 offset:0xc00
	v_mfma_f32_32x32x16_bf16 v[48:63], v[164:167], v[240:243], v[48:63]
	ds_read_b64_tr_b16 v[240:241], v209 offset:0x1400
	ds_read_b64_tr_b16 v[242:243], v209 offset:0x1c00
	v_mfma_f32_32x32x16_bf16 v[48:63], v[168:171], v[244:247], v[48:63]
	ds_read_b64_tr_b16 v[244:245], v209 offset:0x2400
	ds_read_b64_tr_b16 v[246:247], v209 offset:0x2c00
	v_mfma_f32_32x32x16_bf16 v[48:63], v[172:175], v[248:251], v[48:63]
	ds_read_b64_tr_b16 v[248:249], v209 offset:0x3400
	ds_read_b64_tr_b16 v[250:251], v209 offset:0x3c00
	s_waitcnt lgkmcnt(0)
	v_mfma_f32_32x32x16_bf16 v[32:47], v[160:163], v[236:239], v[32:47]
	ds_read_b64_tr_b16 v[236:237], v209 offset:0x600
	ds_read_b64_tr_b16 v[238:239], v209 offset:0xe00
	v_mfma_f32_32x32x16_bf16 v[32:47], v[164:167], v[240:243], v[32:47]
	ds_read_b64_tr_b16 v[240:241], v209 offset:0x1600
	ds_read_b64_tr_b16 v[242:243], v209 offset:0x1e00
	v_mfma_f32_32x32x16_bf16 v[32:47], v[168:171], v[244:247], v[32:47]
	ds_read_b64_tr_b16 v[244:245], v209 offset:0x2600
	ds_read_b64_tr_b16 v[246:247], v209 offset:0x2e00
	v_mfma_f32_32x32x16_bf16 v[32:47], v[172:175], v[248:251], v[32:47]
	ds_read_b64_tr_b16 v[248:249], v209 offset:0x3600
	ds_read_b64_tr_b16 v[250:251], v209 offset:0x3e00
	s_waitcnt lgkmcnt(0)
	v_mfma_f32_32x32x16_bf16 v[16:31], v[160:163], v[236:239], v[16:31]
	s_cmp_gt_i32 s9, s45
	s_cbranch_scc1 .Lattn_mask_0
	v_mov_b32_e32 v160, v80
	v_mov_b32_e32 v80, v76
	v_mov_b32_e32 v76, v77
	v_max_f32_e32 v77, v81, v81
	v_mfma_f32_32x32x16_bf16 v[16:31], v[164:167], v[240:243], v[16:31]
	v_max_f32_e32 v161, v160, v160
	v_max_f32_e32 v77, v161, v77
	v_max3_f32 v77, v77, v82, v83
	v_max3_f32 v77, v77, v84, v85
	v_max3_f32 v77, v77, v86, v87
	v_max3_f32 v77, v77, v88, v89
	v_max3_f32 v77, v77, v90, v91
	v_max3_f32 v77, v77, v92, v93
	v_mfma_f32_32x32x16_bf16 v[16:31], v[168:171], v[244:247], v[16:31]
	v_max3_f32 v77, v77, v94, v95
	v_max3_f32 v77, v77, v64, v65
	v_max3_f32 v77, v77, v66, v67
	v_max3_f32 v77, v77, v68, v69
	v_max3_f32 v77, v77, v70, v71
	v_max3_f32 v77, v77, v72, v73
	v_max3_f32 v77, v77, v74, v75
.Lattn_join_0:
	v_max3_f32 v77, v77, v80, v76
	v_mfma_f32_32x32x16_bf16 v[16:31], v[172:175], v[248:251], v[16:31]
	v_max3_f32 v77, v77, v78, v79
	v_mov_b32_e32 v161, v77
	s_nop 1
	v_permlane32_swap_b32_e32 v77, v161
	v_max_f32_e32 v161, v161, v161
	v_max_f32_e32 v77, v77, v77
	v_max_f32_e32 v77, v77, v161
	v_sub_f32_e32 v161, v77, v210
	v_cmp_ge_f32_e32 vcc, s83, v161
	v_mov_b32_e32 v226, 1.0
	s_cmp_eq_u64 vcc, exec
	s_cbranch_scc0 .LBB0_294

; #define SBAR() __builtin_amdgcn_sched_barrier(0)
; __device__ __forceinline__ void partialSM(f32x16& p0, f32x16& p1, float& m_reg, float& mn, float& alpha, bool msk) {
;     constexpr float C = SCALE * 1.4426950408889634f;
;     if (msk) {
; #pragma unroll
;         for (int r = 0; r < 16; ++r) { p0[r] = -1e30f; p1[r] = -1e30f; }
;     }
;     float pmax = p0[0];
; #pragma unroll
;     for (int r = 1; r < 16; ++r) pmax = fmaxf(pmax, p0[r]);
; #pragma unroll
;     for (int r = 0; r < 16; ++r) pmax = fmaxf(pmax, p1[r]);
;     { auto rr = __builtin_amdgcn_permlane32_swap(__float_as_uint(pmax), __float_as_uint(pmax), false, false);
;       pmax = fmaxf(__uint_as_float(rr[0]), __uint_as_float(rr[1])); }
;     if (__builtin_expect(__all(pmax - m_reg <= THR / SCALE), 1)) { mn = m_reg; alpha = 1.f; }
;     else { mn = fmaxf(m_reg, pmax); alpha = __builtin_amdgcn_exp2f((m_reg - mn) * C); m_reg = mn; }
; template <int D0> __device__ __forceinline__ void pv_one(f32x16& od, int vb, bf16x8 pa0, bf16x8 pa1, bf16x8 pa2, bf16x8 pa3) {
;     const s16x4 l0 = tr_read<v_rd_off(D0, 0, 0)>(vb), h0 = tr_read<v_rd_off(D0, 0, 1)>(vb), l1 = tr_read<v_rd_off(D0, 1, 0)>(vb), h1 = tr_read<v_rd_off(D0, 1, 1)>(vb);
;     const s16x4 l2 = tr_read<v_rd_off(D0, 2, 0)>(vb), h2 = tr_read<v_rd_off(D0, 2, 1)>(vb), l3 = tr_read<v_rd_off(D0, 3, 0)>(vb), h3 = tr_read<v_rd_off(D0, 3, 1)>(vb);
;     asm volatile("s_waitcnt lgkmcnt(0)" ::: "memory"); SBAR();
;     ...
;     od = __builtin_amdgcn_mfma_f32_32x32x16_bf16(pa0, PK(l0, h0), od, 0, 0, 0);
;     od = __builtin_amdgcn_mfma_f32_32x32x16_bf16(pa1, PK(l1, h1), od, 0, 0, 0);
;     od = __builtin_amdgcn_mfma_f32_32x32x16_bf16(pa2, PK(l2, h2), od, 0, 0, 0);
;     od = __builtin_amdgcn_mfma_f32_32x32x16_bf16(pa3, PK(l3, h3), od, 0, 0, 0);
;     ...
; }
; __device__ __forceinline__ void pv_d0(f32x16* o, int vb, bf16x8 pa0, bf16x8 pa1, bf16x8 pa2, bf16x8 pa3) {
;     pv_one<0>(o[0], vb, pa0, pa1, pa2, pa3); pv_one<1>(o[1], vb, pa0, pa1, pa2, pa3); pv_one<2>(o[2], vb, pa0, pa1, pa2, pa3); pv_one<3>(o[3], vb, pa0, pa1, pa2, pa3);
.LBB0_287:
	ds_read_b64_tr_b16 v[198:199], v208 offset:0
	ds_read_b64_tr_b16 v[200:201], v208 offset:0x800
	ds_read_b64_tr_b16 v[230:231], v208 offset:0x1000
	ds_read_b64_tr_b16 v[232:233], v208 offset:0x1800
	ds_read_b64_tr_b16 v[236:237], v208 offset:0x2000
	ds_read_b64_tr_b16 v[238:239], v208 offset:0x2800
	ds_read_b64_tr_b16 v[240:241], v208 offset:0x3000
	ds_read_b64_tr_b16 v[242:243], v208 offset:0x3800
	s_waitcnt lgkmcnt(0)
	s_nop 0
	v_mfma_f32_32x32x16_bf16 v[0:15], v[160:163], v[198:201], v[0:15]
	ds_read_b64_tr_b16 v[198:199], v208 offset:0x200
	ds_read_b64_tr_b16 v[200:201], v208 offset:0xa00
	v_mfma_f32_32x32x16_bf16 v[0:15], v[164:167], v[230:233], v[0:15]
	ds_read_b64_tr_b16 v[230:231], v208 offset:0x1200
	ds_read_b64_tr_b16 v[232:233], v208 offset:0x1a00
	v_mfma_f32_32x32x16_bf16 v[0:15], v[168:171], v[236:239], v[0:15]
	ds_read_b64_tr_b16 v[236:237], v208 offset:0x2200
	ds_read_b64_tr_b16 v[238:239], v208 offset:0x2a00
	v_mfma_f32_32x32x16_bf16 v[0:15], v[172:175], v[240:243], v[0:15]
	ds_read_b64_tr_b16 v[240:241], v208 offset:0x3200
	ds_read_b64_tr_b16 v[242:243], v208 offset:0x3a00
	s_waitcnt lgkmcnt(0)
	v_mfma_f32_32x32x16_bf16 v[48:63], v[160:163], v[198:201], v[48:63]
	ds_read_b64_tr_b16 v[198:199], v208 offset:0x400
	ds_read_b64_tr_b16 v[200:201], v208 offset:0xc00
	v_mfma_f32_32x32x16_bf16 v[48:63], v[164:167], v[230:233], v[48:63]
	ds_read_b64_tr_b16 v[230:231], v208 offset:0x1400
	ds_read_b64_tr_b16 v[232:233], v208 offset:0x1c00
	v_mfma_f32_32x32x16_bf16 v[48:63], v[168:171], v[236:239], v[48:63]
	ds_read_b64_tr_b16 v[236:237], v208 offset:0x2400
	ds_read_b64_tr_b16 v[238:239], v208 offset:0x2c00
	v_mfma_f32_32x32x16_bf16 v[48:63], v[172:175], v[240:243], v[48:63]
	ds_read_b64_tr_b16 v[240:241], v208 offset:0x3400
	ds_read_b64_tr_b16 v[242:243], v208 offset:0x3c00
	s_waitcnt lgkmcnt(0)
	v_mfma_f32_32x32x16_bf16 v[32:47], v[160:163], v[198:201], v[32:47]
	ds_read_b64_tr_b16 v[198:199], v208 offset:0x600
	ds_read_b64_tr_b16 v[200:201], v208 offset:0xe00
	v_mfma_f32_32x32x16_bf16 v[32:47], v[164:167], v[230:233], v[32:47]
	ds_read_b64_tr_b16 v[230:231], v208 offset:0x1600
	ds_read_b64_tr_b16 v[232:233], v208 offset:0x1e00
	v_mfma_f32_32x32x16_bf16 v[32:47], v[168:171], v[236:239], v[32:47]
	ds_read_b64_tr_b16 v[236:237], v208 offset:0x2600
	ds_read_b64_tr_b16 v[238:239], v208 offset:0x2e00
	v_mfma_f32_32x32x16_bf16 v[32:47], v[172:175], v[240:243], v[32:47]
	ds_read_b64_tr_b16 v[240:241], v208 offset:0x3600
	ds_read_b64_tr_b16 v[242:243], v208 offset:0x3e00
	s_waitcnt lgkmcnt(0)
	v_mfma_f32_32x32x16_bf16 v[16:31], v[160:163], v[198:201], v[16:31]
	s_cmp_gt_i32 s25, s45
	s_cbranch_scc1 .Lattn_mask_1
	v_max_f32_e32 v160, v81, v81
	v_max_f32_e32 v161, v80, v80
	v_mfma_f32_32x32x16_bf16 v[16:31], v[164:167], v[230:233], v[16:31]
	v_max_f32_e32 v160, v161, v160
	v_max3_f32 v160, v160, v82, v83
	v_max3_f32 v160, v160, v84, v85
	v_max3_f32 v160, v160, v86, v87
	v_max3_f32 v160, v160, v88, v89
	v_max3_f32 v160, v160, v90, v91
	v_max3_f32 v160, v160, v92, v93
	v_mfma_f32_32x32x16_bf16 v[16:31], v[168:171], v[236:239], v[16:31]
	v_max3_f32 v160, v160, v94, v95
	v_max3_f32 v160, v160, v64, v65
	v_max3_f32 v160, v160, v66, v67
	v_max3_f32 v160, v160, v68, v69
	v_max3_f32 v160, v160, v70, v71
	v_max3_f32 v160, v160, v72, v73
	v_max3_f32 v160, v160, v74, v75
.Lattn_join_1:
	v_max3_f32 v160, v160, v76, v77
	v_mfma_f32_32x32x16_bf16 v[16:31], v[172:175], v[240:243], v[16:31]
	v_max3_f32 v160, v160, v78, v79
	v_mov_b32_e32 v161, v160
	s_nop 1
	v_permlane32_swap_b32_e32 v160, v161
	v_max_f32_e32 v161, v161, v161
	v_max_f32_e32 v160, v160, v160
	v_max_f32_e32 v161, v160, v161
	v_sub_f32_e32 v160, v161, v210
	v_cmp_ge_f32_e32 vcc, s83, v160
	v_mov_b32_e32 v160, 1.0
	s_cmp_eq_u64 vcc, exec
	s_cbranch_scc0 .LBB0_295

; __device__ __forceinline__ void partialSM(f32x16& p0, f32x16& p1, float& m_reg, float& mn, float& alpha, bool msk) {
;     ...
;     if (msk) {
; #pragma unroll
;         for (int r = 0; r < 16; ++r) { p0[r] = -1e30f; p1[r] = -1e30f; }
;     }
;     float pmax = p0[0];
; #pragma unroll
;     for (int r = 1; r < 16; ++r) pmax = fmaxf(pmax, p0[r]);
; #pragma unroll
;     for (int r = 0; r < 16; ++r) pmax = fmaxf(pmax, p1[r]);
.Lattn_mask_1:
	s_mov_b64 vcc, -1
	v_cndmask_b32_e32 v81, v81, v234, vcc
	v_cndmask_b32_e32 v80, v80, v234, vcc
	v_max_f32_e32 v160, v81, v81
	v_max_f32_e32 v161, v80, v80
	v_cndmask_b32_e32 v83, v83, v234, vcc
	v_mfma_f32_32x32x16_bf16 v[16:31], v[164:167], v[230:233], v[16:31]
	v_cndmask_b32_e32 v82, v82, v234, vcc
	v_max_f32_e32 v160, v161, v160
	v_cndmask_b32_e32 v85, v85, v234, vcc
	v_cndmask_b32_e32 v84, v84, v234, vcc
	v_max3_f32 v160, v160, v82, v83
	v_cndmask_b32_e32 v87, v87, v234, vcc
	v_cndmask_b32_e32 v86, v86, v234, vcc
	v_max3_f32 v160, v160, v84, v85
	v_cndmask_b32_e32 v89, v89, v234, vcc
	v_cndmask_b32_e32 v88, v88, v234, vcc
	v_max3_f32 v160, v160, v86, v87
	v_cndmask_b32_e32 v91, v91, v234, vcc
	v_cndmask_b32_e32 v90, v90, v234, vcc
	v_max3_f32 v160, v160, v88, v89
	v_cndmask_b32_e32 v93, v93, v234, vcc
	v_cndmask_b32_e32 v92, v92, v234, vcc
	v_max3_f32 v160, v160, v90, v91
	v_cndmask_b32_e32 v95, v95, v234, vcc
	v_cndmask_b32_e32 v94, v94, v234, vcc
	v_max3_f32 v160, v160, v92, v93
	v_mfma_f32_32x32x16_bf16 v[16:31], v[168:171], v[236:239], v[16:31]
	v_cndmask_b32_e32 v65, v65, v234, vcc
	v_cndmask_b32_e32 v64, v64, v234, vcc
	v_max3_f32 v160, v160, v94, v95
	v_cndmask_b32_e32 v67, v67, v234, vcc
	v_cndmask_b32_e32 v66, v66, v234, vcc
	v_max3_f32 v160, v160, v64, v65
	v_cndmask_b32_e32 v69, v69, v234, vcc
	v_cndmask_b32_e32 v68, v68, v234, vcc
	v_max3_f32 v160, v160, v66, v67
	v_cndmask_b32_e32 v71, v71, v234, vcc
	v_cndmask_b32_e32 v70, v70, v234, vcc
	v_max3_f32 v160, v160, v68, v69
	v_cndmask_b32_e32 v73, v73, v234, vcc
	v_cndmask_b32_e32 v72, v72, v234, vcc
	v_max3_f32 v160, v160, v70, v71
	v_cndmask_b32_e32 v75, v75, v234, vcc
	v_cndmask_b32_e32 v74, v74, v234, vcc
	v_max3_f32 v160, v160, v72, v73
	v_cndmask_b32_e32 v77, v77, v234, vcc
	v_cndmask_b32_e32 v76, v76, v234, vcc
	v_max3_f32 v160, v160, v74, v75
	v_cndmask_b32_e32 v79, v79, v234, vcc
	v_cndmask_b32_e32 v78, v78, v234, vcc
	s_branch .Lattn_join_1
.Lattn_mask_0:
	s_mov_b64 vcc, -1
	v_cndmask_b32_e32 v160, v80, v234, vcc
	v_cndmask_b32_e32 v81, v81, v234, vcc
	v_cndmask_b32_e32 v80, v76, v234, vcc
	v_cndmask_b32_e32 v76, v77, v234, vcc
	v_max_f32_e32 v77, v81, v81
	v_mfma_f32_32x32x16_bf16 v[16:31], v[164:167], v[240:243], v[16:31]
	v_max_f32_e32 v161, v160, v160
	v_cndmask_b32_e32 v82, v82, v234, vcc
	v_cndmask_b32_e32 v83, v83, v234, vcc
	v_max_f32_e32 v77, v161, v77
	v_cndmask_b32_e32 v84, v84, v234, vcc
	v_cndmask_b32_e32 v85, v85, v234, vcc
	v_max3_f32 v77, v77, v82, v83
	v_cndmask_b32_e32 v86, v86, v234, vcc
	v_cndmask_b32_e32 v87, v87, v234, vcc
	v_max3_f32 v77, v77, v84, v85
	v_cndmask_b32_e32 v88, v88, v234, vcc
	v_cndmask_b32_e32 v89, v89, v234, vcc
	v_max3_f32 v77, v77, v86, v87
	v_cndmask_b32_e32 v90, v90, v234, vcc
	v_cndmask_b32_e32 v91, v91, v234, vcc
	v_max3_f32 v77, v77, v88, v89
	v_cndmask_b32_e32 v92, v92, v234, vcc
	v_cndmask_b32_e32 v93, v93, v234, vcc
	v_max3_f32 v77, v77, v90, v91
	v_cndmask_b32_e32 v94, v94, v234, vcc
	v_cndmask_b32_e32 v95, v95, v234, vcc
	v_max3_f32 v77, v77, v92, v93
	v_mfma_f32_32x32x16_bf16 v[16:31], v[168:171], v[244:247], v[16:31]
	v_cndmask_b32_e32 v64, v64, v234, vcc
	v_cndmask_b32_e32 v65, v65, v234, vcc
	v_max3_f32 v77, v77, v94, v95
	v_cndmask_b32_e32 v66, v66, v234, vcc
	v_cndmask_b32_e32 v67, v67, v234, vcc
	v_max3_f32 v77, v77, v64, v65
	v_cndmask_b32_e32 v68, v68, v234, vcc
	v_cndmask_b32_e32 v69, v69, v234, vcc
	v_max3_f32 v77, v77, v66, v67
	v_cndmask_b32_e32 v70, v70, v234, vcc
	v_cndmask_b32_e32 v71, v71, v234, vcc
	v_max3_f32 v77, v77, v68, v69
	v_cndmask_b32_e32 v72, v72, v234, vcc
	v_cndmask_b32_e32 v73, v73, v234, vcc
	v_max3_f32 v77, v77, v70, v71
	v_cndmask_b32_e32 v74, v74, v234, vcc
	v_cndmask_b32_e32 v75, v75, v234, vcc
	v_max3_f32 v77, v77, v72, v73
	v_max3_f32 v77, v77, v74, v75
	v_cndmask_b32_e32 v78, v78, v234, vcc
	v_cndmask_b32_e32 v79, v79, v234, vcc
	s_branch .Lattn_join_0
